# same as previous + code placement restored mod 64 after the edited attention regions
# speedup vs baseline: 1.0135x; 1.0025x over previous
.LBB0_303:
	v_sub_f32_e32 v8, v82, v2
	v_sub_f32_e32 v9, v83, v2
	v_sub_f32_e32 v7, v98, v2
	v_exp_f32_e32 v98, v8
	v_sub_f32_e32 v8, v99, v2
	v_exp_f32_e32 v99, v9
	v_sub_f32_e32 v9, v100, v2
	v_exp_f32_e32 v12, v9
	v_sub_f32_e32 v9, v84, v2
	v_exp_f32_e32 v100, v9
	v_sub_f32_e32 v9, v101, v2
	v_exp_f32_e32 v13, v9
	v_sub_f32_e32 v9, v85, v2
	v_exp_f32_e32 v101, v9
	v_sub_f32_e32 v9, v102, v2
	v_exp_f32_e32 v14, v9
	v_sub_f32_e32 v9, v86, v2
	v_exp_f32_e32 v102, v9
	v_sub_f32_e32 v9, v103, v2
	v_exp_f32_e32 v15, v9
	v_sub_f32_e32 v9, v87, v2
	v_sub_f32_e32 v3, v96, v2
	v_sub_f32_e32 v4, v80, v2
	v_exp_f32_e32 v103, v9
	v_sub_f32_e32 v9, v104, v2
	v_exp_f32_e32 v3, v3
	v_exp_f32_e32 v96, v4
	v_sub_f32_e32 v4, v97, v2
	v_sub_f32_e32 v5, v81, v2
	v_exp_f32_e32 v104, v9
	v_sub_f32_e32 v9, v88, v2
	v_exp_f32_e32 v4, v4
	v_exp_f32_e32 v97, v5
	v_exp_f32_e32 v88, v9
	v_sub_f32_e32 v9, v105, v2
	v_exp_f32_e32 v7, v7
	v_exp_f32_e32 v105, v9
	v_sub_f32_e32 v9, v89, v2
	v_exp_f32_e32 v8, v8
	v_exp_f32_e32 v89, v9
	v_sub_f32_e32 v9, v106, v2
	v_add_f32_e32 v5, v3, v96
	v_exp_f32_e32 v106, v9
	v_sub_f32_e32 v9, v90, v2
	v_add_f32_e32 v5, 0, v5
	v_add_f32_e32 v6, v4, v97
	v_exp_f32_e32 v90, v9
	v_sub_f32_e32 v9, v107, v2
	v_add_f32_e32 v5, v6, v5
	v_add_f32_e32 v6, v7, v98
	v_exp_f32_e32 v107, v9
	v_sub_f32_e32 v9, v91, v2
	v_add_f32_e32 v5, v6, v5
	v_add_f32_e32 v6, v8, v99
	v_exp_f32_e32 v91, v9
	v_sub_f32_e32 v9, v108, v2
	v_add_f32_e32 v5, v6, v5
	v_add_f32_e32 v6, v12, v100
	v_exp_f32_e32 v108, v9
	v_sub_f32_e32 v9, v92, v2
	v_add_f32_e32 v5, v6, v5
	v_add_f32_e32 v6, v13, v101
	v_exp_f32_e32 v92, v9
	v_sub_f32_e32 v9, v109, v2
	v_add_f32_e32 v5, v6, v5
	v_add_f32_e32 v6, v14, v102
	v_exp_f32_e32 v109, v9
	v_sub_f32_e32 v9, v93, v2
	v_add_f32_e32 v5, v6, v5
	v_add_f32_e32 v6, v15, v103
	v_exp_f32_e32 v93, v9
	v_sub_f32_e32 v9, v110, v2
	v_add_f32_e32 v5, v6, v5
	v_add_f32_e32 v6, v104, v88
	v_exp_f32_e32 v110, v9
	v_sub_f32_e32 v9, v94, v2
	v_add_f32_e32 v5, v6, v5
	v_add_f32_e32 v6, v105, v89
	v_exp_f32_e32 v94, v9
	v_sub_f32_e32 v9, v111, v2
	v_add_f32_e32 v5, v6, v5
	v_add_f32_e32 v6, v106, v90
	v_exp_f32_e32 v111, v9
	v_sub_f32_e32 v9, v95, v2
	v_add_f32_e32 v5, v6, v5
	v_add_f32_e32 v6, v107, v91
	v_exp_f32_e32 v95, v9
	v_add_f32_e32 v5, v6, v5
	v_add_f32_e32 v6, v108, v92
	v_add_f32_e32 v5, v6, v5
	v_add_f32_e32 v6, v109, v93
	v_add_f32_e32 v5, v6, v5
	v_add_f32_e32 v6, v110, v94
	v_add_f32_e32 v5, v6, v5
	v_add_f32_e32 v6, v111, v95
	v_add_f32_e32 v212, v6, v5
	v_fmac_f32_e32 v212, v211, v0
	s_add_i32 s2, s52, 0
	s_setprio 0
	v_add_u32_e32 v0, s2, v180
	v_add_u32_e32 v211, s2, v202
	v_cvt_pk_bf16_f32 v4, v3, v4
	v_add3_u32 v3, v0, v203, v202
	v_add3_u32 v86, v211, v204, v180
	v_cvt_pk_bf16_f32 v5, v7, v8
	s_nop 0
	ds_read_b64_tr_b16 v[8:9], v3 offset:32768
	ds_read_b64_tr_b16 v[10:11], v86 offset:34816
	v_cvt_pk_bf16_f32 v6, v12, v13
	v_cvt_pk_bf16_f32 v7, v14, v15
	ds_read_b64_tr_b16 v[12:13], v3 offset:36864
	ds_read_b64_tr_b16 v[80:81], v3 offset:40960
	ds_read_b64_tr_b16 v[84:85], v3 offset:45056
	ds_read_b64_tr_b16 v[14:15], v86 offset:38912
	ds_read_b64_tr_b16 v[82:83], v86 offset:43008
	ds_read_b64_tr_b16 v[86:87], v86 offset:47104
	s_waitcnt lgkmcnt(6)
	v_mfma_f32_32x32x16_bf16 v[64:79], v[8:11], v[4:7], v[64:79]
	v_cvt_pk_bf16_f32 v8, v104, v105
	v_cvt_pk_bf16_f32 v9, v106, v107
	v_cvt_pk_bf16_f32 v10, v108, v109
	v_cvt_pk_bf16_f32 v11, v110, v111
	v_add3_u32 v3, v0, v205, v202
	s_waitcnt lgkmcnt(2)
	v_mfma_f32_32x32x16_bf16 v[64:79], v[12:15], v[8:11], v[64:79]
	v_cvt_pk_bf16_f32 v12, v96, v97
	v_cvt_pk_bf16_f32 v13, v98, v99
	v_cvt_pk_bf16_f32 v14, v100, v101
	v_cvt_pk_bf16_f32 v15, v102, v103
	v_add3_u32 v100, v211, v206, v180
	s_waitcnt lgkmcnt(1)
	v_mfma_f32_32x32x16_bf16 v[64:79], v[80:83], v[12:15], v[64:79]
	v_cvt_pk_bf16_f32 v80, v88, v89
	ds_read_b64_tr_b16 v[88:89], v100 offset:34816
	v_cvt_pk_bf16_f32 v81, v90, v91
	v_cvt_pk_bf16_f32 v82, v92, v93
	v_cvt_pk_bf16_f32 v83, v94, v95
	s_waitcnt lgkmcnt(1)
	s_nop 0
	v_mfma_f32_32x32x16_bf16 v[64:79], v[84:87], v[80:83], v[64:79]
	ds_read_b64_tr_b16 v[86:87], v3 offset:32768
	ds_read_b64_tr_b16 v[90:91], v3 offset:36864
	ds_read_b64_tr_b16 v[94:95], v3 offset:40960
	ds_read_b64_tr_b16 v[98:99], v3 offset:45056
	ds_read_b64_tr_b16 v[92:93], v100 offset:38912
	ds_read_b64_tr_b16 v[96:97], v100 offset:43008
	ds_read_b64_tr_b16 v[100:101], v100 offset:47104
	v_add3_u32 v3, v0, v207, v202
	v_add3_u32 v0, v0, v209, v202
	s_waitcnt lgkmcnt(6)
	v_mfma_f32_32x32x16_bf16 v[48:63], v[86:89], v[4:7], v[48:63]
	s_waitcnt lgkmcnt(2)
	v_mfma_f32_32x32x16_bf16 v[48:63], v[90:93], v[8:11], v[48:63]
	s_waitcnt lgkmcnt(1)
	v_mfma_f32_32x32x16_bf16 v[48:63], v[94:97], v[12:15], v[48:63]
	s_waitcnt lgkmcnt(0)
	v_mfma_f32_32x32x16_bf16 v[48:63], v[98:101], v[80:83], v[48:63]
	v_add3_u32 v98, v211, v208, v180
	ds_read_b64_tr_b16 v[86:87], v98 offset:34816
	ds_read_b64_tr_b16 v[84:85], v3 offset:32768
	ds_read_b64_tr_b16 v[88:89], v3 offset:36864
	ds_read_b64_tr_b16 v[92:93], v3 offset:40960
	ds_read_b64_tr_b16 v[96:97], v3 offset:45056
	ds_read_b64_tr_b16 v[90:91], v98 offset:38912
	ds_read_b64_tr_b16 v[94:95], v98 offset:43008
	ds_read_b64_tr_b16 v[98:99], v98 offset:47104
	v_add3_u32 v3, v211, v210, v180
	v_mov_b32_e32 v211, v212
	s_waitcnt lgkmcnt(6)
	v_mfma_f32_32x32x16_bf16 v[32:47], v[84:87], v[4:7], v[32:47]
	s_waitcnt lgkmcnt(2)
	v_mfma_f32_32x32x16_bf16 v[32:47], v[88:91], v[8:11], v[32:47]
	s_waitcnt lgkmcnt(1)
	v_mfma_f32_32x32x16_bf16 v[32:47], v[92:95], v[12:15], v[32:47]
	s_waitcnt lgkmcnt(0)
	v_mfma_f32_32x32x16_bf16 v[32:47], v[96:99], v[80:83], v[32:47]
	ds_read_b64_tr_b16 v[86:87], v3 offset:34816
	ds_read_b64_tr_b16 v[84:85], v0 offset:32768
	ds_read_b64_tr_b16 v[88:89], v0 offset:36864
	ds_read_b64_tr_b16 v[92:93], v0 offset:40960
	ds_read_b64_tr_b16 v[96:97], v0 offset:45056
	ds_read_b64_tr_b16 v[90:91], v3 offset:38912
	ds_read_b64_tr_b16 v[94:95], v3 offset:43008
	ds_read_b64_tr_b16 v[98:99], v3 offset:47104
	s_waitcnt lgkmcnt(6)
	v_mfma_f32_32x32x16_bf16 v[16:31], v[84:87], v[4:7], v[16:31]
	s_waitcnt lgkmcnt(2)
	v_mfma_f32_32x32x16_bf16 v[16:31], v[88:91], v[8:11], v[16:31]
	s_waitcnt lgkmcnt(1)
	v_mfma_f32_32x32x16_bf16 v[16:31], v[92:95], v[12:15], v[16:31]
	s_waitcnt lgkmcnt(0)
	v_mfma_f32_32x32x16_bf16 v[16:31], v[96:99], v[80:83], v[16:31]
	s_add_i32 s59, s59, 64
	s_addk_i32 s58, 0x4000
	s_cmp_lg_u32 s56, s60
	s_cbranch_scc1 .LBB0_291
	s_nop 0
	s_nop 0
	s_nop 0
	s_nop 0
	s_nop 0
	s_nop 0
	s_nop 0
	s_nop 0

.LBB0_320:
	v_add_u32_e32 v155, s3, v8
	s_andn2_b64 vcc, exec, s[0:1]
	v_ashrrev_i32_e32 v154, s60, v155
	s_cbranch_vccnz .LBB0_395
	v_lshlrev_b32_e32 v160, 2, v156
	v_bfe_u32 v3, v6, 2, 2
	v_lshrrev_b32_e32 v8, 3, v6
	v_bfe_u32 v6, v6, 1, 1
	v_and_or_b32 v6, v8, 2, v6
	v_lshlrev_b32_e32 v8, 2, v3
	v_or_b32_e32 v3, v160, v3
	v_or_b32_e32 v9, v8, v156
	v_lshlrev_b32_e32 v170, 8, v3
	v_bitop3_b32 v3, v8, v6, v156 bitop3:0x36
	v_lshlrev_b32_e32 v10, 3, v152
	v_lshlrev_b32_e32 v172, 4, v3
	v_bitop3_b32 v3, v9, v6, 2 bitop3:0x36
	v_and_b32_e32 v161, 8, v10
	v_xor_b32_e32 v10, v156, v157
	v_lshlrev_b32_e32 v174, 4, v3
	v_or_b32_e32 v3, 4, v6
	v_lshlrev_b32_e32 v162, 4, v10
	v_bitop3_b32 v10, v156, v157, 2 bitop3:0x36
	v_bitop3_b32 v3, v9, v3, 2 bitop3:0x36
	v_lshlrev_b32_e32 v163, 4, v10
	v_bitop3_b32 v10, v156, v157, 4 bitop3:0x36
	v_lshlrev_b32_e32 v177, 4, v3
	v_or_b32_e32 v3, 8, v6
	v_lshlrev_b32_e32 v164, 4, v10
	v_bitop3_b32 v10, v156, v157, 6 bitop3:0x36
	v_bitop3_b32 v8, v6, v9, 4 bitop3:0x36
	v_bitop3_b32 v3, v9, v3, 2 bitop3:0x36
	v_lshlrev_b32_e32 v165, 4, v10
	v_bitop3_b32 v10, v156, v157, 8 bitop3:0x36
	v_lshlrev_b32_e32 v176, 4, v8
	v_bitop3_b32 v8, v6, v9, 8 bitop3:0x36
	v_lshlrev_b32_e32 v179, 4, v3
	v_or_b32_e32 v3, 12, v6
	v_bitop3_b32 v6, v6, v9, 12 bitop3:0x36
	s_add_i32 s75, s75, s3
	v_lshlrev_b32_e32 v166, 4, v10
	v_bitop3_b32 v10, v156, v157, 10 bitop3:0x36
	v_lshlrev_b32_e32 v180, 4, v6
	v_add_u32_e32 v6, s54, v153
	v_lshlrev_b32_e32 v167, 4, v10
	v_bitop3_b32 v10, v156, v157, 12 bitop3:0x36
	v_lshlrev_b32_e32 v178, 4, v8
	v_bitop3_b32 v3, v9, v3, 2 bitop3:0x36
	s_sub_i32 s0, s75, 59
	v_add_u32_e32 v8, 4, v6
	v_lshlrev_b32_e32 v168, 4, v10
	v_bitop3_b32 v10, v156, v157, 14 bitop3:0x36
	v_lshlrev_b32_e32 v181, 4, v3
	v_add_u32_e32 v3, s0, v4
	v_ashrrev_i32_e32 v9, 31, v8
	v_lshlrev_b32_e32 v169, 4, v10
	v_sub_u32_e32 v3, v3, v160
	v_lshl_add_u64 v[8:9], v[8:9], 0, s[52:53]
	v_mov_b64_e32 v[10:11], s[20:21]
	v_subrev_u32_e32 v182, s52, v3
	v_mad_u64_u32 v[12:13], s[0:1], v8, s62, v[10:11]
	v_and_b32_e32 v3, 15, v7
	v_mad_i32_i24 v13, v9, s62, v13
	v_lshlrev_b32_e32 v8, 4, v3
	v_mov_b32_e32 v3, v1
	v_lshl_add_u64 v[2:3], v[12:13], 0, v[2:3]
	v_ashrrev_i32_e32 v7, 31, v6
	v_lshl_add_u64 v[146:147], s[18:19], 0, v[2:3]
	v_lshl_add_u64 v[2:3], v[6:7], 0, s[52:53]
	v_mad_u64_u32 v[6:7], s[0:1], v2, s62, v[10:11]
	v_and_b32_e32 v2, 15, v5
	v_mad_i32_i24 v7, v3, s62, v7
	v_lshlrev_b32_e32 v2, 4, v2
	v_mov_b32_e32 v3, v1
	v_mov_b32_e32 v9, v1
	v_lshl_add_u64 v[2:3], v[6:7], 0, v[2:3]
	v_lshl_add_u64 v[8:9], v[12:13], 0, v[8:9]
	v_lshl_add_u64 v[148:149], s[14:15], 0, v[2:3]
	v_lshl_add_u64 v[2:3], v[6:7], 0, v[0:1]
	v_mov_b32_e32 v14, v1
	v_mov_b32_e32 v15, v1
	v_lshl_add_u64 v[144:145], s[14:15], 0, v[8:9]
	v_lshl_add_u64 v[150:151], s[18:19], 0, v[2:3]
	v_mov_b32_e32 v0, v1
	v_mov_b32_e32 v2, v1
	v_mov_b32_e32 v3, v1
	v_mov_b32_e32 v4, v1
	v_mov_b32_e32 v5, v1
	v_mov_b32_e32 v6, v1
	v_mov_b32_e32 v7, v1
	v_mov_b32_e32 v8, v1
	v_mov_b32_e32 v9, v1
	v_mov_b32_e32 v10, v1
	v_mov_b32_e32 v11, v1
	v_mov_b32_e32 v12, v1
	v_mov_b32_e32 v13, v1
	v_mov_b64_e32 v[78:79], v[14:15]
	v_mov_b64_e32 v[62:63], v[14:15]
	v_mov_b64_e32 v[46:47], v[14:15]
	v_mov_b64_e32 v[30:31], v[14:15]
	s_or_b32 s97, s75, 31
	s_add_i32 s96, s75, 0xffffff80
	s_ashr_i32 s76, s75, s60
	v_add_u32_e32 v159, 0, v158
	s_mov_b32 s66, 1
	s_mov_b32 s3, s21
	s_mov_b32 s20, 0
	v_mov_b32_e32 v183, 0
	v_mov_b32_e32 v184, 0xf149f2ca
	v_mov_b64_e32 v[76:77], v[12:13]
	v_mov_b64_e32 v[74:75], v[10:11]
	v_mov_b64_e32 v[72:73], v[8:9]
	v_mov_b64_e32 v[70:71], v[6:7]
	v_mov_b64_e32 v[68:69], v[4:5]
	v_mov_b64_e32 v[66:67], v[2:3]
	v_mov_b64_e32 v[64:65], v[0:1]
	v_mov_b64_e32 v[60:61], v[12:13]
	v_mov_b64_e32 v[58:59], v[10:11]
	v_mov_b64_e32 v[56:57], v[8:9]
	v_mov_b64_e32 v[54:55], v[6:7]
	v_mov_b64_e32 v[52:53], v[4:5]
	v_mov_b64_e32 v[50:51], v[2:3]
	v_mov_b64_e32 v[48:49], v[0:1]
	v_mov_b64_e32 v[44:45], v[12:13]
	v_mov_b64_e32 v[42:43], v[10:11]
	v_mov_b64_e32 v[40:41], v[8:9]
	v_mov_b64_e32 v[38:39], v[6:7]
	v_mov_b64_e32 v[36:37], v[4:5]
	v_mov_b64_e32 v[34:35], v[2:3]
	v_mov_b64_e32 v[32:33], v[0:1]
	v_mov_b64_e32 v[28:29], v[12:13]
	v_mov_b64_e32 v[26:27], v[10:11]
	v_mov_b64_e32 v[24:25], v[8:9]
	v_mov_b64_e32 v[22:23], v[6:7]
	v_mov_b64_e32 v[20:21], v[4:5]
	v_mov_b64_e32 v[18:19], v[2:3]
	v_mov_b64_e32 v[16:17], v[0:1]
	s_lshl_b32 s0, 1, s60
	s_add_i32 s0, s0, -1
	v_and_b32_e32 v254, s0, v155
	v_min_u32_e32 v254, 0x80, v254
	s_waitcnt vmcnt(0)
	s_nop 0
	s_nop 0
	s_nop 0
	s_nop 0
	s_nop 0
	s_nop 0
	s_nop 0
	s_nop 0
	s_nop 0
	s_nop 0
	s_nop 0

.LBB0_391:
	v_sub_f32_e32 v13, v13, v96
	v_sub_f32_e32 v80, v80, v96
	v_exp_f32_e32 v13, v13
	v_exp_f32_e32 v99, v80
	v_sub_f32_e32 v80, v97, v96
	v_sub_f32_e32 v81, v81, v96
	v_exp_f32_e32 v80, v80
	v_exp_f32_e32 v97, v81
	v_add_f32_e32 v81, v99, v13
	v_sub_f32_e32 v14, v14, v96
	v_sub_f32_e32 v82, v82, v96
	v_add_f32_e32 v81, 0, v81
	v_add_f32_e32 v100, v97, v80
	v_exp_f32_e32 v14, v14
	v_exp_f32_e32 v101, v82
	v_sub_f32_e32 v82, v98, v96
	v_sub_f32_e32 v83, v83, v96
	v_sub_f32_e32 v84, v84, v96
	v_exp_f32_e32 v82, v82
	v_exp_f32_e32 v98, v83
	v_add_f32_e32 v81, v100, v81
	v_sub_f32_e32 v11, v11, v96
	v_exp_f32_e32 v100, v84
	v_sub_f32_e32 v84, v85, v96
	v_sub_f32_e32 v9, v9, v96
	v_exp_f32_e32 v11, v11
	v_sub_f32_e32 v15, v15, v96
	v_exp_f32_e32 v102, v84
	v_exp_f32_e32 v84, v9
	v_sub_f32_e32 v9, v86, v96
	v_exp_f32_e32 v15, v15
	v_exp_f32_e32 v103, v9
	v_sub_f32_e32 v9, v12, v96
	v_sub_f32_e32 v7, v7, v96
	v_add_f32_e32 v83, v101, v14
	v_exp_f32_e32 v12, v9
	v_sub_f32_e32 v9, v87, v96
	v_exp_f32_e32 v105, v7
	v_sub_f32_e32 v7, v88, v96
	v_add_f32_e32 v81, v83, v81
	v_add_f32_e32 v83, v98, v82
	v_exp_f32_e32 v104, v9
	v_exp_f32_e32 v88, v7
	v_sub_f32_e32 v7, v10, v96
	v_sub_f32_e32 v5, v5, v96
	v_add_f32_e32 v81, v83, v81
	v_add_f32_e32 v83, v100, v11
	v_exp_f32_e32 v106, v7
	v_sub_f32_e32 v7, v89, v96
	v_exp_f32_e32 v107, v5
	v_sub_f32_e32 v5, v90, v96
	v_add_f32_e32 v81, v83, v81
	v_add_f32_e32 v83, v102, v15
	v_exp_f32_e32 v89, v7
	v_exp_f32_e32 v90, v5
	v_sub_f32_e32 v5, v8, v96
	v_sub_f32_e32 v3, v3, v96
	v_add_f32_e32 v9, v83, v81
	v_add_f32_e32 v81, v103, v84
	v_exp_f32_e32 v108, v5
	v_sub_f32_e32 v5, v91, v96
	v_exp_f32_e32 v109, v3
	v_sub_f32_e32 v3, v92, v96
	v_add_f32_e32 v9, v81, v9
	v_add_f32_e32 v81, v104, v12
	v_exp_f32_e32 v91, v5
	v_exp_f32_e32 v92, v3
	v_sub_f32_e32 v3, v6, v96
	v_sub_f32_e32 v2, v2, v96
	v_add_f32_e32 v7, v81, v9
	v_add_f32_e32 v9, v88, v105
	v_exp_f32_e32 v110, v3
	v_sub_f32_e32 v3, v93, v96
	v_exp_f32_e32 v111, v2
	v_sub_f32_e32 v2, v94, v96
	v_add_f32_e32 v7, v9, v7
	v_add_f32_e32 v9, v89, v106
	v_exp_f32_e32 v93, v3
	v_exp_f32_e32 v94, v2
	v_sub_f32_e32 v2, v4, v96
	v_add_f32_e32 v5, v9, v7
	v_add_f32_e32 v7, v90, v107
	v_exp_f32_e32 v184, v2
	v_sub_f32_e32 v2, v95, v96
	v_add_f32_e32 v5, v7, v5
	v_add_f32_e32 v7, v91, v108
	v_exp_f32_e32 v95, v2
	v_add_f32_e32 v3, v7, v5
	v_add_f32_e32 v5, v92, v109
	v_add_f32_e32 v3, v5, v3
	v_add_f32_e32 v5, v93, v110
	v_add_f32_e32 v2, v5, v3
	v_add_f32_e32 v3, v94, v111
	v_add_f32_e32 v2, v3, v2
	v_add_f32_e32 v3, v95, v184
	v_add_f32_e32 v185, v3, v2
	v_fmac_f32_e32 v185, v183, v0
	s_add_i32 s0, s53, 0
	s_setprio 0
	v_cvt_pk_bf16_f32 v3, v14, v82
	v_add_u32_e32 v0, s0, v161
	v_add_u32_e32 v14, s0, v170
	v_cvt_pk_bf16_f32 v2, v13, v80
	v_add3_u32 v13, v0, v172, v170
	v_add3_u32 v86, v14, v174, v161
	s_nop 0
	ds_read_b64_tr_b16 v[6:7], v13 offset:32768
	ds_read_b64_tr_b16 v[8:9], v86 offset:34816
	v_cvt_pk_bf16_f32 v4, v11, v15
	v_cvt_pk_bf16_f32 v5, v84, v12
	ds_read_b64_tr_b16 v[10:11], v13 offset:36864
	ds_read_b64_tr_b16 v[80:81], v13 offset:40960
	ds_read_b64_tr_b16 v[84:85], v13 offset:45056
	ds_read_b64_tr_b16 v[12:13], v86 offset:38912
	ds_read_b64_tr_b16 v[82:83], v86 offset:43008
	ds_read_b64_tr_b16 v[86:87], v86 offset:47104
	s_waitcnt lgkmcnt(6)
	v_mfma_f32_32x32x16_bf16 v[64:79], v[6:9], v[2:5], v[64:79]
	v_cvt_pk_bf16_f32 v6, v105, v106
	v_cvt_pk_bf16_f32 v7, v107, v108
	v_cvt_pk_bf16_f32 v8, v109, v110
	v_cvt_pk_bf16_f32 v9, v111, v184
	v_add3_u32 v15, v0, v176, v170
	v_mov_b32_e32 v183, v185
	s_waitcnt lgkmcnt(2)
	v_mfma_f32_32x32x16_bf16 v[64:79], v[10:13], v[6:9], v[64:79]
	v_cvt_pk_bf16_f32 v10, v99, v97
	v_cvt_pk_bf16_f32 v11, v101, v98
	v_cvt_pk_bf16_f32 v12, v100, v102
	v_cvt_pk_bf16_f32 v13, v103, v104
	v_add3_u32 v97, v14, v179, v161
	s_waitcnt lgkmcnt(1)
	v_mfma_f32_32x32x16_bf16 v[64:79], v[80:83], v[10:13], v[64:79]
	v_cvt_pk_bf16_f32 v83, v94, v95
	v_add3_u32 v94, v14, v177, v161
	v_cvt_pk_bf16_f32 v80, v88, v89
	ds_read_b64_tr_b16 v[88:89], v94 offset:34816
	v_cvt_pk_bf16_f32 v81, v90, v91
	v_cvt_pk_bf16_f32 v82, v92, v93
	v_add3_u32 v14, v14, v181, v161
	s_waitcnt lgkmcnt(1)
	v_mfma_f32_32x32x16_bf16 v[64:79], v[84:87], v[80:83], v[64:79]
	ds_read_b64_tr_b16 v[86:87], v15 offset:32768
	ds_read_b64_tr_b16 v[90:91], v15 offset:36864
	ds_read_b64_tr_b16 v[98:99], v15 offset:40960
	ds_read_b64_tr_b16 v[102:103], v15 offset:45056
	ds_read_b64_tr_b16 v[92:93], v94 offset:38912
	ds_read_b64_tr_b16 v[100:101], v94 offset:43008
	ds_read_b64_tr_b16 v[104:105], v94 offset:47104
	v_add3_u32 v15, v0, v178, v170
	v_add3_u32 v0, v0, v180, v170
	s_waitcnt lgkmcnt(6)
	v_mfma_f32_32x32x16_bf16 v[48:63], v[86:89], v[2:5], v[48:63]
	s_waitcnt lgkmcnt(2)
	v_mfma_f32_32x32x16_bf16 v[48:63], v[90:93], v[6:9], v[48:63]
	s_waitcnt lgkmcnt(1)
	v_mfma_f32_32x32x16_bf16 v[48:63], v[98:101], v[10:13], v[48:63]
	ds_read_b64_tr_b16 v[86:87], v97 offset:34816
	ds_read_b64_tr_b16 v[84:85], v15 offset:32768
	ds_read_b64_tr_b16 v[88:89], v15 offset:36864
	ds_read_b64_tr_b16 v[92:93], v15 offset:40960
	ds_read_b64_tr_b16 v[98:99], v15 offset:45056
	ds_read_b64_tr_b16 v[90:91], v97 offset:38912
	ds_read_b64_tr_b16 v[94:95], v97 offset:43008
	ds_read_b64_tr_b16 v[100:101], v97 offset:47104
	s_waitcnt lgkmcnt(6)
	v_mfma_f32_32x32x16_bf16 v[32:47], v[84:87], v[2:5], v[32:47]
	s_waitcnt lgkmcnt(2)
	v_mfma_f32_32x32x16_bf16 v[32:47], v[88:91], v[6:9], v[32:47]
	s_waitcnt lgkmcnt(1)
	v_mfma_f32_32x32x16_bf16 v[32:47], v[92:95], v[10:13], v[32:47]
	s_waitcnt lgkmcnt(0)
	v_mfma_f32_32x32x16_bf16 v[32:47], v[98:101], v[80:83], v[32:47]
	ds_read_b64_tr_b16 v[86:87], v14 offset:34816
	ds_read_b64_tr_b16 v[84:85], v0 offset:32768
	ds_read_b64_tr_b16 v[88:89], v0 offset:36864
	ds_read_b64_tr_b16 v[92:93], v0 offset:40960
	ds_read_b64_tr_b16 v[98:99], v0 offset:45056
	ds_read_b64_tr_b16 v[90:91], v14 offset:38912
	ds_read_b64_tr_b16 v[94:95], v14 offset:43008
	ds_read_b64_tr_b16 v[100:101], v14 offset:47104
	s_waitcnt lgkmcnt(6)
	v_mfma_f32_32x32x16_bf16 v[16:31], v[84:87], v[2:5], v[16:31]
	s_waitcnt lgkmcnt(2)
	v_mfma_f32_32x32x16_bf16 v[16:31], v[88:91], v[6:9], v[16:31]
	s_waitcnt lgkmcnt(1)
	v_mfma_f32_32x32x16_bf16 v[16:31], v[92:95], v[10:13], v[16:31]
	v_mfma_f32_32x32x16_bf16 v[48:63], v[102:105], v[80:83], v[48:63]
	s_waitcnt lgkmcnt(0)
	v_mfma_f32_32x32x16_bf16 v[16:31], v[98:101], v[80:83], v[16:31]
	s_branch .LBB0_393

.LBB0_395:
	v_mov_b32_e32 v14, v1
	v_mov_b32_e32 v15, v1
	v_mov_b32_e32 v0, v1
	v_mov_b32_e32 v2, v1
	v_mov_b32_e32 v3, v1
	v_mov_b32_e32 v4, v1
	v_mov_b32_e32 v5, v1
	v_mov_b32_e32 v6, v1
	v_mov_b32_e32 v7, v1
	v_mov_b32_e32 v8, v1
	v_mov_b32_e32 v9, v1
	v_mov_b32_e32 v10, v1
	v_mov_b32_e32 v11, v1
	v_mov_b32_e32 v12, v1
	v_mov_b32_e32 v13, v1
	v_mov_b64_e32 v[30:31], v[14:15]
	v_mov_b64_e32 v[46:47], v[14:15]
	v_mov_b64_e32 v[62:63], v[14:15]
	v_mov_b64_e32 v[78:79], v[14:15]
	v_mov_b32_e32 v183, 0
	v_mov_b32_e32 v96, 0xf149f2ca
	v_mov_b64_e32 v[28:29], v[12:13]
	v_mov_b64_e32 v[26:27], v[10:11]
	v_mov_b64_e32 v[24:25], v[8:9]
	v_mov_b64_e32 v[22:23], v[6:7]
	v_mov_b64_e32 v[20:21], v[4:5]
	v_mov_b64_e32 v[18:19], v[2:3]
	v_mov_b64_e32 v[16:17], v[0:1]
	v_mov_b64_e32 v[44:45], v[12:13]
	v_mov_b64_e32 v[42:43], v[10:11]
	v_mov_b64_e32 v[40:41], v[8:9]
	v_mov_b64_e32 v[38:39], v[6:7]
	v_mov_b64_e32 v[36:37], v[4:5]
	v_mov_b64_e32 v[34:35], v[2:3]
	v_mov_b64_e32 v[32:33], v[0:1]
	v_mov_b64_e32 v[60:61], v[12:13]
	v_mov_b64_e32 v[58:59], v[10:11]
	v_mov_b64_e32 v[56:57], v[8:9]
	v_mov_b64_e32 v[54:55], v[6:7]
	v_mov_b64_e32 v[52:53], v[4:5]
	v_mov_b64_e32 v[50:51], v[2:3]
	v_mov_b64_e32 v[48:49], v[0:1]
	v_mov_b64_e32 v[76:77], v[12:13]
	v_mov_b64_e32 v[74:75], v[10:11]
	v_mov_b64_e32 v[72:73], v[8:9]
	v_mov_b64_e32 v[70:71], v[6:7]
	v_mov_b64_e32 v[68:69], v[4:5]
	v_mov_b64_e32 v[66:67], v[2:3]
	v_mov_b64_e32 v[64:65], v[0:1]
	s_branch .LBB0_397
	s_nop 0
	s_nop 0
	s_nop 0
	s_nop 0
	s_nop 0
	s_nop 0
	s_nop 0
	s_nop 0
	s_nop 0
	s_nop 0
	s_nop 0
	s_nop 0

.LBB0_435:
	v_sub_f32_e32 v8, v82, v2
	v_sub_f32_e32 v9, v83, v2
	v_sub_f32_e32 v7, v98, v2
	v_exp_f32_e32 v98, v8
	v_sub_f32_e32 v8, v99, v2
	v_exp_f32_e32 v99, v9
	v_sub_f32_e32 v9, v100, v2
	v_exp_f32_e32 v12, v9
	v_sub_f32_e32 v9, v84, v2
	v_exp_f32_e32 v100, v9
	v_sub_f32_e32 v9, v101, v2
	v_exp_f32_e32 v13, v9
	v_sub_f32_e32 v9, v85, v2
	v_exp_f32_e32 v101, v9
	v_sub_f32_e32 v9, v102, v2
	v_exp_f32_e32 v14, v9
	v_sub_f32_e32 v9, v86, v2
	v_exp_f32_e32 v102, v9
	v_sub_f32_e32 v9, v103, v2
	v_exp_f32_e32 v15, v9
	v_sub_f32_e32 v9, v87, v2
	v_sub_f32_e32 v3, v96, v2
	v_sub_f32_e32 v4, v80, v2
	v_exp_f32_e32 v103, v9
	v_sub_f32_e32 v9, v104, v2
	v_exp_f32_e32 v3, v3
	v_exp_f32_e32 v96, v4
	v_sub_f32_e32 v4, v97, v2
	v_sub_f32_e32 v5, v81, v2
	v_exp_f32_e32 v104, v9
	v_sub_f32_e32 v9, v88, v2
	v_exp_f32_e32 v4, v4
	v_exp_f32_e32 v97, v5
	v_exp_f32_e32 v88, v9
	v_sub_f32_e32 v9, v105, v2
	v_exp_f32_e32 v7, v7
	v_exp_f32_e32 v105, v9
	v_sub_f32_e32 v9, v89, v2
	v_exp_f32_e32 v8, v8
	v_exp_f32_e32 v89, v9
	v_sub_f32_e32 v9, v106, v2
	v_add_f32_e32 v5, v3, v96
	v_exp_f32_e32 v106, v9
	v_sub_f32_e32 v9, v90, v2
	v_add_f32_e32 v5, 0, v5
	v_add_f32_e32 v6, v4, v97
	v_exp_f32_e32 v90, v9
	v_sub_f32_e32 v9, v107, v2
	v_add_f32_e32 v5, v6, v5
	v_add_f32_e32 v6, v7, v98
	v_exp_f32_e32 v107, v9
	v_sub_f32_e32 v9, v91, v2
	v_add_f32_e32 v5, v6, v5
	v_add_f32_e32 v6, v8, v99
	v_exp_f32_e32 v91, v9
	v_sub_f32_e32 v9, v108, v2
	v_add_f32_e32 v5, v6, v5
	v_add_f32_e32 v6, v12, v100
	v_exp_f32_e32 v108, v9
	v_sub_f32_e32 v9, v92, v2
	v_add_f32_e32 v5, v6, v5
	v_add_f32_e32 v6, v13, v101
	v_exp_f32_e32 v92, v9
	v_sub_f32_e32 v9, v109, v2
	v_add_f32_e32 v5, v6, v5
	v_add_f32_e32 v6, v14, v102
	v_exp_f32_e32 v109, v9
	v_sub_f32_e32 v9, v93, v2
	v_add_f32_e32 v5, v6, v5
	v_add_f32_e32 v6, v15, v103
	v_exp_f32_e32 v93, v9
	v_sub_f32_e32 v9, v110, v2
	v_add_f32_e32 v5, v6, v5
	v_add_f32_e32 v6, v104, v88
	v_exp_f32_e32 v110, v9
	v_sub_f32_e32 v9, v94, v2
	v_add_f32_e32 v5, v6, v5
	v_add_f32_e32 v6, v105, v89
	v_exp_f32_e32 v94, v9
	v_sub_f32_e32 v9, v111, v2
	v_add_f32_e32 v5, v6, v5
	v_add_f32_e32 v6, v106, v90
	v_exp_f32_e32 v111, v9
	v_sub_f32_e32 v9, v95, v2
	v_add_f32_e32 v5, v6, v5
	v_add_f32_e32 v6, v107, v91
	v_exp_f32_e32 v95, v9
	v_add_f32_e32 v5, v6, v5
	v_add_f32_e32 v6, v108, v92
	v_add_f32_e32 v5, v6, v5
	v_add_f32_e32 v6, v109, v93
	v_add_f32_e32 v5, v6, v5
	v_add_f32_e32 v6, v110, v94
	v_add_f32_e32 v5, v6, v5
	v_add_f32_e32 v6, v111, v95
	v_add_f32_e32 v213, v6, v5
	v_fmac_f32_e32 v213, v212, v0
	s_add_i32 s0, s2, 0
	s_setprio 0
	v_add_u32_e32 v0, s0, v181
	v_add_u32_e32 v212, s0, v203
	v_cvt_pk_bf16_f32 v4, v3, v4
	v_add3_u32 v3, v0, v204, v203
	v_add3_u32 v86, v212, v205, v181
	v_cvt_pk_bf16_f32 v5, v7, v8
	s_nop 0
	ds_read_b64_tr_b16 v[8:9], v3 offset:32768
	ds_read_b64_tr_b16 v[10:11], v86 offset:34816
	v_cvt_pk_bf16_f32 v6, v12, v13
	v_cvt_pk_bf16_f32 v7, v14, v15
	ds_read_b64_tr_b16 v[12:13], v3 offset:36864
	ds_read_b64_tr_b16 v[80:81], v3 offset:40960
	ds_read_b64_tr_b16 v[84:85], v3 offset:45056
	ds_read_b64_tr_b16 v[14:15], v86 offset:38912
	ds_read_b64_tr_b16 v[82:83], v86 offset:43008
	ds_read_b64_tr_b16 v[86:87], v86 offset:47104
	s_waitcnt lgkmcnt(6)
	v_mfma_f32_32x32x16_bf16 v[64:79], v[8:11], v[4:7], v[64:79]
	v_cvt_pk_bf16_f32 v8, v104, v105
	v_cvt_pk_bf16_f32 v9, v106, v107
	v_cvt_pk_bf16_f32 v10, v108, v109
	v_cvt_pk_bf16_f32 v11, v110, v111
	v_add3_u32 v3, v0, v206, v203
	s_waitcnt lgkmcnt(2)
	v_mfma_f32_32x32x16_bf16 v[64:79], v[12:15], v[8:11], v[64:79]
	v_cvt_pk_bf16_f32 v12, v96, v97
	v_cvt_pk_bf16_f32 v13, v98, v99
	v_cvt_pk_bf16_f32 v14, v100, v101
	v_cvt_pk_bf16_f32 v15, v102, v103
	v_add3_u32 v100, v212, v207, v181
	s_waitcnt lgkmcnt(1)
	v_mfma_f32_32x32x16_bf16 v[64:79], v[80:83], v[12:15], v[64:79]
	v_cvt_pk_bf16_f32 v80, v88, v89
	ds_read_b64_tr_b16 v[88:89], v100 offset:34816
	v_cvt_pk_bf16_f32 v81, v90, v91
	v_cvt_pk_bf16_f32 v82, v92, v93
	v_cvt_pk_bf16_f32 v83, v94, v95
	s_waitcnt lgkmcnt(1)
	s_nop 0
	v_mfma_f32_32x32x16_bf16 v[64:79], v[84:87], v[80:83], v[64:79]
	ds_read_b64_tr_b16 v[86:87], v3 offset:32768
	ds_read_b64_tr_b16 v[90:91], v3 offset:36864
	ds_read_b64_tr_b16 v[94:95], v3 offset:40960
	ds_read_b64_tr_b16 v[98:99], v3 offset:45056
	ds_read_b64_tr_b16 v[92:93], v100 offset:38912
	ds_read_b64_tr_b16 v[96:97], v100 offset:43008
	ds_read_b64_tr_b16 v[100:101], v100 offset:47104
	v_add3_u32 v3, v0, v208, v203
	v_add3_u32 v0, v0, v210, v203
	s_waitcnt lgkmcnt(6)
	v_mfma_f32_32x32x16_bf16 v[48:63], v[86:89], v[4:7], v[48:63]
	s_waitcnt lgkmcnt(2)
	v_mfma_f32_32x32x16_bf16 v[48:63], v[90:93], v[8:11], v[48:63]
	s_waitcnt lgkmcnt(1)
	v_mfma_f32_32x32x16_bf16 v[48:63], v[94:97], v[12:15], v[48:63]
	s_waitcnt lgkmcnt(0)
	v_mfma_f32_32x32x16_bf16 v[48:63], v[98:101], v[80:83], v[48:63]
	v_add3_u32 v98, v212, v209, v181
	ds_read_b64_tr_b16 v[86:87], v98 offset:34816
	ds_read_b64_tr_b16 v[84:85], v3 offset:32768
	ds_read_b64_tr_b16 v[88:89], v3 offset:36864
	ds_read_b64_tr_b16 v[92:93], v3 offset:40960
	ds_read_b64_tr_b16 v[96:97], v3 offset:45056
	ds_read_b64_tr_b16 v[90:91], v98 offset:38912
	ds_read_b64_tr_b16 v[94:95], v98 offset:43008
	ds_read_b64_tr_b16 v[98:99], v98 offset:47104
	v_add3_u32 v3, v212, v211, v181
	v_mov_b32_e32 v212, v213
	s_waitcnt lgkmcnt(6)
	v_mfma_f32_32x32x16_bf16 v[32:47], v[84:87], v[4:7], v[32:47]
	s_waitcnt lgkmcnt(2)
	v_mfma_f32_32x32x16_bf16 v[32:47], v[88:91], v[8:11], v[32:47]
	s_waitcnt lgkmcnt(1)
	v_mfma_f32_32x32x16_bf16 v[32:47], v[92:95], v[12:15], v[32:47]
	s_waitcnt lgkmcnt(0)
	v_mfma_f32_32x32x16_bf16 v[32:47], v[96:99], v[80:83], v[32:47]
	ds_read_b64_tr_b16 v[86:87], v3 offset:34816
	ds_read_b64_tr_b16 v[84:85], v0 offset:32768
	ds_read_b64_tr_b16 v[88:89], v0 offset:36864
	ds_read_b64_tr_b16 v[92:93], v0 offset:40960
	ds_read_b64_tr_b16 v[96:97], v0 offset:45056
	ds_read_b64_tr_b16 v[90:91], v3 offset:38912
	ds_read_b64_tr_b16 v[94:95], v3 offset:43008
	ds_read_b64_tr_b16 v[98:99], v3 offset:47104
	s_waitcnt lgkmcnt(6)
	v_mfma_f32_32x32x16_bf16 v[16:31], v[84:87], v[4:7], v[16:31]
	s_waitcnt lgkmcnt(2)
	v_mfma_f32_32x32x16_bf16 v[16:31], v[88:91], v[8:11], v[16:31]
	s_waitcnt lgkmcnt(1)
	v_mfma_f32_32x32x16_bf16 v[16:31], v[92:95], v[12:15], v[16:31]
	s_waitcnt lgkmcnt(0)
	v_mfma_f32_32x32x16_bf16 v[16:31], v[96:99], v[80:83], v[16:31]
	s_add_i32 s57, s57, 64
	s_addk_i32 s55, 0x4000
	s_cmp_lg_u32 s56, s58
	s_cbranch_scc1 .LBB0_423
	s_nop 0
	s_nop 0
	s_nop 0
	s_nop 0
	s_nop 0
	s_nop 0
	s_nop 0
	s_nop 0

.LBB0_468:
	v_sub_f32_e32 v8, v82, v2
	v_sub_f32_e32 v9, v83, v2
	v_sub_f32_e32 v7, v98, v2
	v_exp_f32_e32 v98, v8
	v_sub_f32_e32 v8, v99, v2
	v_exp_f32_e32 v99, v9
	v_sub_f32_e32 v9, v100, v2
	v_exp_f32_e32 v12, v9
	v_sub_f32_e32 v9, v84, v2
	v_exp_f32_e32 v100, v9
	v_sub_f32_e32 v9, v101, v2
	v_exp_f32_e32 v13, v9
	v_sub_f32_e32 v9, v85, v2
	v_exp_f32_e32 v101, v9
	v_sub_f32_e32 v9, v102, v2
	v_exp_f32_e32 v14, v9
	v_sub_f32_e32 v9, v86, v2
	v_exp_f32_e32 v102, v9
	v_sub_f32_e32 v9, v103, v2
	v_exp_f32_e32 v15, v9
	v_sub_f32_e32 v9, v87, v2
	v_sub_f32_e32 v3, v96, v2
	v_sub_f32_e32 v4, v80, v2
	v_exp_f32_e32 v103, v9
	v_sub_f32_e32 v9, v104, v2
	v_exp_f32_e32 v3, v3
	v_exp_f32_e32 v96, v4
	v_sub_f32_e32 v4, v97, v2
	v_sub_f32_e32 v5, v81, v2
	v_exp_f32_e32 v104, v9
	v_sub_f32_e32 v9, v88, v2
	v_exp_f32_e32 v4, v4
	v_exp_f32_e32 v97, v5
	v_exp_f32_e32 v88, v9
	v_sub_f32_e32 v9, v105, v2
	v_exp_f32_e32 v7, v7
	v_exp_f32_e32 v105, v9
	v_sub_f32_e32 v9, v89, v2
	v_exp_f32_e32 v8, v8
	v_exp_f32_e32 v89, v9
	v_sub_f32_e32 v9, v106, v2
	v_add_f32_e32 v5, v3, v96
	v_exp_f32_e32 v106, v9
	v_sub_f32_e32 v9, v90, v2
	v_add_f32_e32 v5, 0, v5
	v_add_f32_e32 v6, v4, v97
	v_exp_f32_e32 v90, v9
	v_sub_f32_e32 v9, v107, v2
	v_add_f32_e32 v5, v6, v5
	v_add_f32_e32 v6, v7, v98
	v_exp_f32_e32 v107, v9
	v_sub_f32_e32 v9, v91, v2
	v_add_f32_e32 v5, v6, v5
	v_add_f32_e32 v6, v8, v99
	v_exp_f32_e32 v91, v9
	v_sub_f32_e32 v9, v108, v2
	v_add_f32_e32 v5, v6, v5
	v_add_f32_e32 v6, v12, v100
	v_exp_f32_e32 v108, v9
	v_sub_f32_e32 v9, v92, v2
	v_add_f32_e32 v5, v6, v5
	v_add_f32_e32 v6, v13, v101
	v_exp_f32_e32 v92, v9
	v_sub_f32_e32 v9, v109, v2
	v_add_f32_e32 v5, v6, v5
	v_add_f32_e32 v6, v14, v102
	v_exp_f32_e32 v109, v9
	v_sub_f32_e32 v9, v93, v2
	v_add_f32_e32 v5, v6, v5
	v_add_f32_e32 v6, v15, v103
	v_exp_f32_e32 v93, v9
	v_sub_f32_e32 v9, v110, v2
	v_add_f32_e32 v5, v6, v5
	v_add_f32_e32 v6, v104, v88
	v_exp_f32_e32 v110, v9
	v_sub_f32_e32 v9, v94, v2
	v_add_f32_e32 v5, v6, v5
	v_add_f32_e32 v6, v105, v89
	v_exp_f32_e32 v94, v9
	v_sub_f32_e32 v9, v111, v2
	v_add_f32_e32 v5, v6, v5
	v_add_f32_e32 v6, v106, v90
	v_exp_f32_e32 v111, v9
	v_sub_f32_e32 v9, v95, v2
	v_add_f32_e32 v5, v6, v5
	v_add_f32_e32 v6, v107, v91
	v_exp_f32_e32 v95, v9
	v_add_f32_e32 v5, v6, v5
	v_add_f32_e32 v6, v108, v92
	v_add_f32_e32 v5, v6, v5
	v_add_f32_e32 v6, v109, v93
	v_add_f32_e32 v5, v6, v5
	v_add_f32_e32 v6, v110, v94
	v_add_f32_e32 v5, v6, v5
	v_add_f32_e32 v6, v111, v95
	v_add_f32_e32 v213, v6, v5
	v_fmac_f32_e32 v213, v212, v0
	s_add_i32 s0, s2, 0
	s_setprio 0
	v_add_u32_e32 v0, s0, v181
	v_add_u32_e32 v212, s0, v203
	v_cvt_pk_bf16_f32 v4, v3, v4
	v_add3_u32 v3, v0, v204, v203
	v_add3_u32 v86, v212, v205, v181
	v_cvt_pk_bf16_f32 v5, v7, v8
	s_nop 0
	ds_read_b64_tr_b16 v[8:9], v3 offset:32768
	ds_read_b64_tr_b16 v[10:11], v86 offset:34816
	v_cvt_pk_bf16_f32 v6, v12, v13
	v_cvt_pk_bf16_f32 v7, v14, v15
	ds_read_b64_tr_b16 v[12:13], v3 offset:36864
	ds_read_b64_tr_b16 v[80:81], v3 offset:40960
	ds_read_b64_tr_b16 v[84:85], v3 offset:45056
	ds_read_b64_tr_b16 v[14:15], v86 offset:38912
	ds_read_b64_tr_b16 v[82:83], v86 offset:43008
	ds_read_b64_tr_b16 v[86:87], v86 offset:47104
	s_waitcnt lgkmcnt(6)
	v_mfma_f32_32x32x16_bf16 v[64:79], v[8:11], v[4:7], v[64:79]
	v_cvt_pk_bf16_f32 v8, v104, v105
	v_cvt_pk_bf16_f32 v9, v106, v107
	v_cvt_pk_bf16_f32 v10, v108, v109
	v_cvt_pk_bf16_f32 v11, v110, v111
	v_add3_u32 v3, v0, v206, v203
	s_waitcnt lgkmcnt(2)
	v_mfma_f32_32x32x16_bf16 v[64:79], v[12:15], v[8:11], v[64:79]
	v_cvt_pk_bf16_f32 v12, v96, v97
	v_cvt_pk_bf16_f32 v13, v98, v99
	v_cvt_pk_bf16_f32 v14, v100, v101
	v_cvt_pk_bf16_f32 v15, v102, v103
	v_add3_u32 v100, v212, v207, v181
	s_waitcnt lgkmcnt(1)
	v_mfma_f32_32x32x16_bf16 v[64:79], v[80:83], v[12:15], v[64:79]
	v_cvt_pk_bf16_f32 v80, v88, v89
	ds_read_b64_tr_b16 v[88:89], v100 offset:34816
	v_cvt_pk_bf16_f32 v81, v90, v91
	v_cvt_pk_bf16_f32 v82, v92, v93
	v_cvt_pk_bf16_f32 v83, v94, v95
	s_waitcnt lgkmcnt(1)
	s_nop 0
	v_mfma_f32_32x32x16_bf16 v[64:79], v[84:87], v[80:83], v[64:79]
	ds_read_b64_tr_b16 v[86:87], v3 offset:32768
	ds_read_b64_tr_b16 v[90:91], v3 offset:36864
	ds_read_b64_tr_b16 v[94:95], v3 offset:40960
	ds_read_b64_tr_b16 v[98:99], v3 offset:45056
	ds_read_b64_tr_b16 v[92:93], v100 offset:38912
	ds_read_b64_tr_b16 v[96:97], v100 offset:43008
	ds_read_b64_tr_b16 v[100:101], v100 offset:47104
	v_add3_u32 v3, v0, v208, v203
	v_add3_u32 v0, v0, v210, v203
	s_waitcnt lgkmcnt(6)
	v_mfma_f32_32x32x16_bf16 v[48:63], v[86:89], v[4:7], v[48:63]
	s_waitcnt lgkmcnt(2)
	v_mfma_f32_32x32x16_bf16 v[48:63], v[90:93], v[8:11], v[48:63]
	s_waitcnt lgkmcnt(1)
	v_mfma_f32_32x32x16_bf16 v[48:63], v[94:97], v[12:15], v[48:63]
	s_waitcnt lgkmcnt(0)
	v_mfma_f32_32x32x16_bf16 v[48:63], v[98:101], v[80:83], v[48:63]
	v_add3_u32 v98, v212, v209, v181
	ds_read_b64_tr_b16 v[86:87], v98 offset:34816
	ds_read_b64_tr_b16 v[84:85], v3 offset:32768
	ds_read_b64_tr_b16 v[88:89], v3 offset:36864
	ds_read_b64_tr_b16 v[92:93], v3 offset:40960
	ds_read_b64_tr_b16 v[96:97], v3 offset:45056
	ds_read_b64_tr_b16 v[90:91], v98 offset:38912
	ds_read_b64_tr_b16 v[94:95], v98 offset:43008
	ds_read_b64_tr_b16 v[98:99], v98 offset:47104
	v_add3_u32 v3, v212, v211, v181
	v_mov_b32_e32 v212, v213
	s_waitcnt lgkmcnt(6)
	v_mfma_f32_32x32x16_bf16 v[32:47], v[84:87], v[4:7], v[32:47]
	s_waitcnt lgkmcnt(2)
	v_mfma_f32_32x32x16_bf16 v[32:47], v[88:91], v[8:11], v[32:47]
	s_waitcnt lgkmcnt(1)
	v_mfma_f32_32x32x16_bf16 v[32:47], v[92:95], v[12:15], v[32:47]
	s_waitcnt lgkmcnt(0)
	v_mfma_f32_32x32x16_bf16 v[32:47], v[96:99], v[80:83], v[32:47]
	ds_read_b64_tr_b16 v[86:87], v3 offset:34816
	ds_read_b64_tr_b16 v[84:85], v0 offset:32768
	ds_read_b64_tr_b16 v[88:89], v0 offset:36864
	ds_read_b64_tr_b16 v[92:93], v0 offset:40960
	ds_read_b64_tr_b16 v[96:97], v0 offset:45056
	ds_read_b64_tr_b16 v[90:91], v3 offset:38912
	ds_read_b64_tr_b16 v[94:95], v3 offset:43008
	ds_read_b64_tr_b16 v[98:99], v3 offset:47104
	s_waitcnt lgkmcnt(6)
	v_mfma_f32_32x32x16_bf16 v[16:31], v[84:87], v[4:7], v[16:31]
	s_waitcnt lgkmcnt(2)
	v_mfma_f32_32x32x16_bf16 v[16:31], v[88:91], v[8:11], v[16:31]
	s_waitcnt lgkmcnt(1)
	v_mfma_f32_32x32x16_bf16 v[16:31], v[92:95], v[12:15], v[16:31]
	s_waitcnt lgkmcnt(0)
	v_mfma_f32_32x32x16_bf16 v[16:31], v[96:99], v[80:83], v[16:31]
	s_add_i32 s57, s57, 64
	s_addk_i32 s55, 0x4000
	s_cmp_lg_u32 s56, s58
	s_cbranch_scc1 .LBB0_456
	s_branch .LBB0_262

.LBB0_476:
	v_mov_b32_e32 v66, v0
	s_nop 1
	v_permlane32_swap_b32_e32 v0, v66
	v_add_f32_e32 v0, v0, v66
	v_div_scale_f32 v66, s[0:1], v0, v0, 1.0
	v_rcp_f32_e32 v68, v66
	s_waitcnt vmcnt(0)
	s_mulk_i32 s55, 0x1400
	s_mul_hi_u32 s0, s54, 0x1400
	v_fma_f32 v67, -v66, v68, 1.0
	v_fmac_f32_e32 v68, v67, v68
	v_div_scale_f32 v67, vcc, 1.0, v0, 1.0
	v_mul_f32_e32 v69, v67, v68
	v_fma_f32 v70, -v66, v69, v67
	v_fmac_f32_e32 v69, v70, v68
	v_fma_f32 v70, -v66, v69, v67
	v_lshlrev_b32_e32 v66, 8, v204
	v_add3_u32 v71, s53, v66, v205
	v_lshlrev_b32_e32 v66, 4, v203
	v_and_b32_e32 v72, 0xf0, v66
	v_add_u32_e32 v73, v71, v72
	ds_read_b64 v[66:67], v73
	v_div_fmas_f32 v68, v70, v68, v69
	v_div_fixup_f32 v0, v68, v0, 1.0
	v_pk_mul_f32 v[50:51], v[50:51], v[0:1] op_sel_hi:[1,0]
	v_pk_mul_f32 v[52:53], v[52:53], v[0:1] op_sel_hi:[1,0]
	s_waitcnt lgkmcnt(0)
	v_lshlrev_b32_e32 v68, 16, v66
	v_and_b32_e32 v69, 0xffff0000, v66
	v_lshlrev_b32_e32 v66, 16, v67
	v_and_b32_e32 v67, 0xffff0000, v67
	v_pk_mul_f32 v[50:51], v[50:51], v[68:69]
	v_pk_mul_f32 v[52:53], v[52:53], v[66:67]
	v_cvt_pk_bf16_f32 v50, v50, v51
	v_cvt_pk_bf16_f32 v51, v52, v53
	ds_write_b64 v73, v[50:51]
	v_xad_u32 v66, v72, 16, v71
	ds_read_b64 v[50:51], v66
	v_pk_mul_f32 v[52:53], v[54:55], v[0:1] op_sel_hi:[1,0]
	v_pk_mul_f32 v[34:35], v[34:35], v[0:1] op_sel_hi:[1,0]
	v_pk_mul_f32 v[36:37], v[36:37], v[0:1] op_sel_hi:[1,0]
	v_pk_mul_f32 v[18:19], v[18:19], v[0:1] op_sel_hi:[1,0]
	s_waitcnt lgkmcnt(0)
	v_lshlrev_b32_e32 v54, 16, v50
	v_and_b32_e32 v55, 0xffff0000, v50
	v_pk_mul_f32 v[52:53], v[52:53], v[54:55]
	v_lshlrev_b32_e32 v54, 16, v51
	v_cvt_pk_bf16_f32 v50, v52, v53
	v_pk_mul_f32 v[52:53], v[56:57], v[0:1] op_sel_hi:[1,0]
	v_and_b32_e32 v55, 0xffff0000, v51
	v_pk_mul_f32 v[52:53], v[52:53], v[54:55]
	v_xad_u32 v56, v72, 32, v71
	v_cvt_pk_bf16_f32 v51, v52, v53
	ds_write_b64 v66, v[50:51]
	ds_read_b64 v[50:51], v56
	v_pk_mul_f32 v[52:53], v[58:59], v[0:1] op_sel_hi:[1,0]
	v_pk_mul_f32 v[20:21], v[20:21], v[0:1] op_sel_hi:[1,0]
	v_pk_mul_f32 v[2:3], v[2:3], v[0:1] op_sel_hi:[1,0]
	v_pk_mul_f32 v[4:5], v[4:5], v[0:1] op_sel_hi:[1,0]
	s_waitcnt lgkmcnt(0)
	v_lshlrev_b32_e32 v54, 16, v50
	v_and_b32_e32 v55, 0xffff0000, v50
	v_pk_mul_f32 v[52:53], v[52:53], v[54:55]
	v_lshlrev_b32_e32 v54, 16, v51
	v_cvt_pk_bf16_f32 v50, v52, v53
	v_pk_mul_f32 v[52:53], v[60:61], v[0:1] op_sel_hi:[1,0]
	v_and_b32_e32 v55, 0xffff0000, v51
	v_pk_mul_f32 v[52:53], v[52:53], v[54:55]
	s_add_i32 s0, s0, s55
	v_cvt_pk_bf16_f32 v51, v52, v53
	ds_write_b64 v56, v[50:51]
	v_xad_u32 v56, v72, 48, v71
	ds_read_b64 v[50:51], v56
	v_pk_mul_f32 v[52:53], v[62:63], v[0:1] op_sel_hi:[1,0]
	s_mulk_i32 s54, 0x1400
	s_add_u32 s1, s30, s54
	s_addc_u32 s0, s31, s0
	s_waitcnt lgkmcnt(0)
	v_lshlrev_b32_e32 v54, 16, v50
	v_and_b32_e32 v55, 0xffff0000, v50
	v_pk_mul_f32 v[52:53], v[52:53], v[54:55]
	v_lshlrev_b32_e32 v54, 16, v51
	v_cvt_pk_bf16_f32 v50, v52, v53
	v_pk_mul_f32 v[52:53], v[64:65], v[0:1] op_sel_hi:[1,0]
	v_and_b32_e32 v55, 0xffff0000, v51
	v_pk_mul_f32 v[52:53], v[52:53], v[54:55]
	v_xad_u32 v54, v72, 64, v71
	v_cvt_pk_bf16_f32 v51, v52, v53
	ds_write_b64 v56, v[50:51]
	ds_read_b64 v[50:51], v54
	s_lshl_b32 s2, s52, 1
	s_add_u32 s1, s1, s2
	s_addc_u32 s2, s0, 0
	s_lshl_b32 s0, s20, 1
	s_waitcnt lgkmcnt(0)
	v_lshlrev_b32_e32 v52, 16, v50
	v_and_b32_e32 v53, 0xffff0000, v50
	v_lshlrev_b32_e32 v50, 16, v51
	v_and_b32_e32 v51, 0xffff0000, v51
	v_pk_mul_f32 v[34:35], v[34:35], v[52:53]
	v_pk_mul_f32 v[36:37], v[36:37], v[50:51]
	v_cvt_pk_bf16_f32 v34, v34, v35
	v_cvt_pk_bf16_f32 v35, v36, v37
	ds_write_b64 v54, v[34:35]
	v_xad_u32 v50, v72, s69, v71
	ds_read_b64 v[34:35], v50
	v_pk_mul_f32 v[36:37], v[38:39], v[0:1] op_sel_hi:[1,0]
	s_add_u32 s0, s1, s0
	s_addc_u32 s1, s2, 0
	s_mov_b64 s[2:3], -1
	s_waitcnt lgkmcnt(0)
	v_lshlrev_b32_e32 v38, 16, v34
	v_and_b32_e32 v39, 0xffff0000, v34
	v_pk_mul_f32 v[36:37], v[36:37], v[38:39]
	v_lshlrev_b32_e32 v38, 16, v35
	v_cvt_pk_bf16_f32 v34, v36, v37
	v_pk_mul_f32 v[36:37], v[40:41], v[0:1] op_sel_hi:[1,0]
	v_and_b32_e32 v39, 0xffff0000, v35
	v_pk_mul_f32 v[36:37], v[36:37], v[38:39]
	v_xad_u32 v40, v72, s70, v71
	v_cvt_pk_bf16_f32 v35, v36, v37
	ds_write_b64 v50, v[34:35]
	ds_read_b64 v[34:35], v40
	v_pk_mul_f32 v[36:37], v[42:43], v[0:1] op_sel_hi:[1,0]
	s_waitcnt lgkmcnt(0)
	v_lshlrev_b32_e32 v38, 16, v34
	v_and_b32_e32 v39, 0xffff0000, v34
	v_pk_mul_f32 v[36:37], v[36:37], v[38:39]
	v_lshlrev_b32_e32 v38, 16, v35
	v_cvt_pk_bf16_f32 v34, v36, v37
	v_pk_mul_f32 v[36:37], v[44:45], v[0:1] op_sel_hi:[1,0]
	v_and_b32_e32 v39, 0xffff0000, v35
	v_pk_mul_f32 v[36:37], v[36:37], v[38:39]
	s_nop 0
	v_cvt_pk_bf16_f32 v35, v36, v37
	ds_write_b64 v40, v[34:35]
	v_xad_u32 v40, v72, s71, v71
	ds_read_b64 v[34:35], v40
	v_pk_mul_f32 v[36:37], v[46:47], v[0:1] op_sel_hi:[1,0]
	s_waitcnt lgkmcnt(0)
	v_lshlrev_b32_e32 v38, 16, v34
	v_and_b32_e32 v39, 0xffff0000, v34
	v_pk_mul_f32 v[36:37], v[36:37], v[38:39]
	v_lshlrev_b32_e32 v38, 16, v35
	v_cvt_pk_bf16_f32 v34, v36, v37
	v_pk_mul_f32 v[36:37], v[48:49], v[0:1] op_sel_hi:[1,0]
	v_and_b32_e32 v39, 0xffff0000, v35
	v_pk_mul_f32 v[36:37], v[36:37], v[38:39]
	v_xad_u32 v38, v72, s72, v71
	v_cvt_pk_bf16_f32 v35, v36, v37
	ds_write_b64 v40, v[34:35]
	ds_read_b64 v[34:35], v38
	s_waitcnt lgkmcnt(0)
	v_lshlrev_b32_e32 v36, 16, v34
	v_and_b32_e32 v37, 0xffff0000, v34
	v_lshlrev_b32_e32 v34, 16, v35
	v_and_b32_e32 v35, 0xffff0000, v35
	v_pk_mul_f32 v[18:19], v[18:19], v[36:37]
	v_pk_mul_f32 v[20:21], v[20:21], v[34:35]
	v_cvt_pk_bf16_f32 v18, v18, v19
	v_cvt_pk_bf16_f32 v19, v20, v21
	ds_write_b64 v38, v[18:19]
	v_xad_u32 v34, v72, s73, v71
	ds_read_b64 v[18:19], v34
	v_pk_mul_f32 v[20:21], v[22:23], v[0:1] op_sel_hi:[1,0]
	s_waitcnt lgkmcnt(0)
	v_lshlrev_b32_e32 v22, 16, v18
	v_and_b32_e32 v23, 0xffff0000, v18
	v_pk_mul_f32 v[20:21], v[20:21], v[22:23]
	v_lshlrev_b32_e32 v22, 16, v19
	v_cvt_pk_bf16_f32 v18, v20, v21
	v_pk_mul_f32 v[20:21], v[24:25], v[0:1] op_sel_hi:[1,0]
	v_and_b32_e32 v23, 0xffff0000, v19
	v_pk_mul_f32 v[20:21], v[20:21], v[22:23]
	v_xad_u32 v24, v72, s79, v71
	v_cvt_pk_bf16_f32 v19, v20, v21
	ds_write_b64 v34, v[18:19]
	ds_read_b64 v[18:19], v24
	v_pk_mul_f32 v[20:21], v[26:27], v[0:1] op_sel_hi:[1,0]
	s_waitcnt lgkmcnt(0)
	v_lshlrev_b32_e32 v22, 16, v18
	v_and_b32_e32 v23, 0xffff0000, v18
	v_pk_mul_f32 v[20:21], v[20:21], v[22:23]
	v_lshlrev_b32_e32 v22, 16, v19
	v_cvt_pk_bf16_f32 v18, v20, v21
	v_pk_mul_f32 v[20:21], v[28:29], v[0:1] op_sel_hi:[1,0]
	v_and_b32_e32 v23, 0xffff0000, v19
	v_pk_mul_f32 v[20:21], v[20:21], v[22:23]
	s_nop 0
	v_cvt_pk_bf16_f32 v19, v20, v21
	ds_write_b64 v24, v[18:19]
	v_xad_u32 v24, v72, s80, v71
	ds_read_b64 v[18:19], v24
	v_pk_mul_f32 v[20:21], v[30:31], v[0:1] op_sel_hi:[1,0]
	s_waitcnt lgkmcnt(0)
	v_lshlrev_b32_e32 v22, 16, v18
	v_and_b32_e32 v23, 0xffff0000, v18
	v_pk_mul_f32 v[20:21], v[20:21], v[22:23]
	v_lshlrev_b32_e32 v22, 16, v19
	v_cvt_pk_bf16_f32 v18, v20, v21
	v_pk_mul_f32 v[20:21], v[32:33], v[0:1] op_sel_hi:[1,0]
	v_and_b32_e32 v23, 0xffff0000, v19
	v_pk_mul_f32 v[20:21], v[20:21], v[22:23]
	v_xad_u32 v22, v72, s81, v71
	v_cvt_pk_bf16_f32 v19, v20, v21
	ds_write_b64 v24, v[18:19]
	ds_read_b64 v[18:19], v22
	s_waitcnt lgkmcnt(0)
	v_lshlrev_b32_e32 v20, 16, v18
	v_and_b32_e32 v21, 0xffff0000, v18
	v_lshlrev_b32_e32 v18, 16, v19
	v_and_b32_e32 v19, 0xffff0000, v19
	v_pk_mul_f32 v[2:3], v[2:3], v[20:21]
	v_pk_mul_f32 v[4:5], v[4:5], v[18:19]
	v_cvt_pk_bf16_f32 v2, v2, v3
	v_cvt_pk_bf16_f32 v3, v4, v5
	ds_write_b64 v22, v[2:3]
	v_xad_u32 v18, v72, s82, v71
	ds_read_b64 v[2:3], v18
	v_pk_mul_f32 v[4:5], v[6:7], v[0:1] op_sel_hi:[1,0]
	v_add_u32_e32 v20, s53, v72
	s_waitcnt lgkmcnt(0)
	v_lshlrev_b32_e32 v6, 16, v2
	v_and_b32_e32 v7, 0xffff0000, v2
	v_pk_mul_f32 v[4:5], v[4:5], v[6:7]
	v_lshlrev_b32_e32 v6, 16, v3
	v_cvt_pk_bf16_f32 v2, v4, v5
	v_pk_mul_f32 v[4:5], v[8:9], v[0:1] op_sel_hi:[1,0]
	v_and_b32_e32 v7, 0xffff0000, v3
	v_pk_mul_f32 v[4:5], v[4:5], v[6:7]
	v_xad_u32 v8, v72, s83, v71
	v_cvt_pk_bf16_f32 v3, v4, v5
	ds_write_b64 v18, v[2:3]
	ds_read_b64 v[2:3], v8
	v_pk_mul_f32 v[4:5], v[10:11], v[0:1] op_sel_hi:[1,0]
	s_waitcnt lgkmcnt(0)
	v_lshlrev_b32_e32 v6, 16, v2
	v_and_b32_e32 v7, 0xffff0000, v2
	v_pk_mul_f32 v[4:5], v[4:5], v[6:7]
	v_lshlrev_b32_e32 v6, 16, v3
	v_cvt_pk_bf16_f32 v2, v4, v5
	v_pk_mul_f32 v[4:5], v[12:13], v[0:1] op_sel_hi:[1,0]
	v_and_b32_e32 v7, 0xffff0000, v3
	v_pk_mul_f32 v[4:5], v[4:5], v[6:7]
	s_nop 0
	v_cvt_pk_bf16_f32 v3, v4, v5
	ds_write_b64 v8, v[2:3]
	v_xad_u32 v8, v72, s84, v71
	ds_read_b64 v[2:3], v8
	v_pk_mul_f32 v[4:5], v[14:15], v[0:1] op_sel_hi:[1,0]
	s_waitcnt lgkmcnt(0)
	v_lshlrev_b32_e32 v6, 16, v2
	v_and_b32_e32 v7, 0xffff0000, v2
	v_pk_mul_f32 v[4:5], v[4:5], v[6:7]
	v_lshlrev_b32_e32 v6, 16, v3
	v_cvt_pk_bf16_f32 v2, v4, v5
	v_pk_mul_f32 v[4:5], v[16:17], v[0:1] op_sel_hi:[1,0]
	v_and_b32_e32 v7, 0xffff0000, v3
	v_pk_mul_f32 v[4:5], v[4:5], v[6:7]
	v_lshl_add_u32 v6, v169, 8, v20
	v_cvt_pk_bf16_f32 v3, v4, v5
	ds_write_b64 v8, v[2:3]
	s_waitcnt lgkmcnt(0)
	ds_read_b128 v[2:5], v6
	v_mul_u32_u24_e32 v0, 0xa00, v169
	v_lshlrev_b32_e32 v0, 1, v0
	v_lshl_add_u64 v[14:15], s[0:1], 0, v[0:1]
	v_lshlrev_b32_e32 v16, 1, v172
	v_mov_b32_e32 v17, v1
	v_lshl_add_u64 v[10:11], v[14:15], 0, v[16:17]
	s_waitcnt lgkmcnt(0)
	global_store_dwordx4 v[10:11], v[2:5], off offset:3072
	v_lshlrev_b32_e32 v10, 1, v162
	v_mov_b32_e32 v11, v1
	v_lshl_add_u32 v2, v163, 8, v20
	ds_read_b128 v[6:9], v6 offset:4096
	ds_read_b128 v[2:5], v2
	v_lshl_add_u64 v[10:11], v[14:15], 0, v[10:11]
	v_add_co_u32_e32 v18, vcc, s86, v10
	v_lshl_add_u32 v10, v165, 8, v20
	s_nop 0
	v_addc_co_u32_e32 v19, vcc, 0, v11, vcc
	ds_read_b128 v[10:13], v10
	s_waitcnt lgkmcnt(1)
	global_store_dwordx4 v[18:19], v[2:5], off offset:3072
	v_lshl_add_u64 v[14:15], v[14:15], 0, s[48:49]
	s_nop 0
	v_lshlrev_b32_e32 v2, 1, v164
	v_mov_b32_e32 v3, v1
	v_lshl_add_u64 v[2:3], v[14:15], 0, v[2:3]
	s_waitcnt lgkmcnt(0)
	global_store_dwordx4 v[2:3], v[10:13], off offset:3072
	v_lshl_add_u32 v2, v167, 8, v20
	ds_read_b128 v[2:5], v2
	v_lshlrev_b32_e32 v10, 1, v166
	v_mov_b32_e32 v11, v1
	v_lshl_add_u64 v[10:11], v[14:15], 0, v[10:11]
	v_add_co_u32_e32 v14, vcc, s86, v10
	v_lshl_add_u32 v10, v201, 8, v20
	s_nop 0
	v_addc_co_u32_e32 v15, vcc, 0, v11, vcc
	ds_read_b128 v[10:13], v10
	s_waitcnt lgkmcnt(1)
	global_store_dwordx4 v[14:15], v[2:5], off offset:3072
	s_nop 1
	v_add_u32_e32 v2, 0x14000, v0
	v_mov_b32_e32 v3, v1
	v_lshl_add_u64 v[2:3], s[0:1], 0, v[2:3]
	v_lshl_add_u64 v[2:3], v[2:3], 0, v[16:17]
	global_store_dwordx4 v[2:3], v[6:9], off offset:3072
	v_add_u32_e32 v2, 0x19000, v0
	v_mov_b32_e32 v3, v1
	v_lshl_add_u64 v[2:3], s[0:1], 0, v[2:3]
	v_lshlrev_b32_e32 v4, 1, v168
	v_mov_b32_e32 v5, v1
	v_lshl_add_u64 v[2:3], v[2:3], 0, v[4:5]
	s_waitcnt lgkmcnt(0)
	global_store_dwordx4 v[2:3], v[10:13], off offset:3072
	v_lshl_add_u32 v2, v200, 8, v20
	v_add_u32_e32 v6, 0x1e000, v0
	v_mov_b32_e32 v7, v1
	ds_read_b128 v[2:5], v2
	v_lshl_add_u64 v[6:7], s[0:1], 0, v[6:7]
	v_lshlrev_b32_e32 v8, 1, v170
	v_mov_b32_e32 v9, v1
	v_lshl_add_u64 v[10:11], v[6:7], 0, v[8:9]
	v_lshl_add_u32 v6, v202, 8, v20
	ds_read_b128 v[6:9], v6
	v_add_u32_e32 v0, 0x23000, v0
	s_waitcnt lgkmcnt(1)
	global_store_dwordx4 v[10:11], v[2:5], off offset:3072
	s_nop 1
	v_lshl_add_u64 v[2:3], s[0:1], 0, v[0:1]
	v_lshlrev_b32_e32 v0, 1, v174
	v_lshl_add_u64 v[2:3], v[2:3], 0, v[0:1]
	s_waitcnt lgkmcnt(0)
	global_store_dwordx4 v[2:3], v[6:9], off offset:3072
	s_waitcnt lgkmcnt(0)
	s_cbranch_execz .LBB0_318
	s_branch .LBB0_400
	s_nop 0
	s_nop 0
	s_nop 0
	s_nop 0
	s_nop 0
	s_nop 0
	s_nop 0
	s_nop 0
